# DFT tile K-loop: LDS-DMA issue sequences interleaved between the step's MFMAs
# speedup vs baseline: 1.1228x; 1.0034x over previous
; #define G_WAIT() { asm volatile("s_waitcnt vmcnt(0)" ::: "memory"); __syncthreads(); }
;     ...
;   G_DMA(0, 0);
;   G_WAIT();
;   for (int kt = 0; kt < nk; kt += 2) {
;     if (kt + 1 < nk) G_DMA(1, kt + 1);
;     G_COMPUTE(0);
;     G_WAIT();
;     if (kt + 1 < nk) {
;       if (kt + 2 < nk) G_DMA(0, kt + 2);
;       G_COMPUTE(1);
.LBB0_168:
	v_add_u32_e32 v160, v98, v96
	v_add_u32_e32 v192, v97, v96
	v_add_u32_e32 v161, v98, v99
	v_add_u32_e32 v193, v97, v99
	v_add_u32_e32 v190, v98, v100
	v_add_u32_e32 v194, v97, v100
	v_add_u32_e32 v191, v98, v101
	v_add_u32_e32 v195, v97, v101
	ds_read_b128 v[128:131], v160 offset:16384
	ds_read_b128 v[132:135], v160 offset:20480
	ds_read_b128 v[136:139], v192 offset:0
	ds_read_b128 v[140:143], v192 offset:4096
	ds_read_b128 v[144:147], v161 offset:16384
	ds_read_b128 v[148:151], v161 offset:20480
	ds_read_b128 v[152:155], v193 offset:0
	ds_read_b128 v[156:159], v193 offset:4096
	ds_read_b128 v[216:219], v190 offset:16384
	ds_read_b128 v[220:223], v190 offset:20480
	ds_read_b128 v[224:227], v194 offset:0
	ds_read_b128 v[228:231], v194 offset:4096
	ds_read_b128 v[232:235], v191 offset:16384
	ds_read_b128 v[236:239], v191 offset:20480
	ds_read_b128 v[240:243], v195 offset:0
	ds_read_b128 v[244:247], v195 offset:4096
	s_waitcnt lgkmcnt(0)
	s_barrier
	s_cmp_lt_u32 s35, s5
	s_cbranch_scc0 .Ldl_s0_nodma
	v_add_u32_e32 v250, 0x0, v86
	v_lshl_add_u64 v[248:249], v[80:81], 0, v[0:1]
	v_readfirstlane_b32 s48, v250
	v_lshl_add_u64 v[248:249], v[248:249], 0, s[22:23]
	s_mov_b32 m0, s48
	s_nop 0
	global_load_lds_dwordx4 v[248:249], off
	v_mfma_f32_32x32x16_bf16 v[50:65], v[128:131], v[136:139], v[50:65]
	v_mfma_f32_32x32x16_bf16 v[34:49], v[132:135], v[136:139], v[34:49]
	v_add_u32_e32 v250, 0x4000, v86
	v_lshl_add_u64 v[248:249], v[72:73], 0, v[0:1]
	v_readfirstlane_b32 s48, v250
	v_lshl_add_u64 v[248:249], v[248:249], 0, s[22:23]
	s_mov_b32 m0, s48
	s_nop 0
	global_load_lds_dwordx4 v[248:249], off
	v_mfma_f32_32x32x16_bf16 v[18:33], v[128:131], v[140:143], v[18:33]
	v_mfma_f32_32x32x16_bf16 v[2:17], v[132:135], v[140:143], v[2:17]
	v_add_u32_e32 v250, 0x1000, v86
	v_lshl_add_u64 v[248:249], v[78:79], 0, v[0:1]
	v_readfirstlane_b32 s48, v250
	v_lshl_add_u64 v[248:249], v[248:249], 0, s[22:23]
	s_mov_b32 m0, s48
	s_nop 0
	global_load_lds_dwordx4 v[248:249], off
	v_mfma_f32_32x32x16_bf16 v[50:65], v[144:147], v[152:155], v[50:65]
	v_mfma_f32_32x32x16_bf16 v[34:49], v[148:151], v[152:155], v[34:49]
	v_add_u32_e32 v250, 0x5000, v86
	v_lshl_add_u64 v[248:249], v[70:71], 0, v[0:1]
	v_readfirstlane_b32 s48, v250
	v_lshl_add_u64 v[248:249], v[248:249], 0, s[22:23]
	s_mov_b32 m0, s48
	s_nop 0
	global_load_lds_dwordx4 v[248:249], off
	v_mfma_f32_32x32x16_bf16 v[18:33], v[144:147], v[156:159], v[18:33]
	v_mfma_f32_32x32x16_bf16 v[2:17], v[148:151], v[156:159], v[2:17]
	v_add_u32_e32 v250, 0x2000, v86
	v_lshl_add_u64 v[248:249], v[74:75], 0, v[0:1]
	v_readfirstlane_b32 s48, v250
	v_lshl_add_u64 v[248:249], v[248:249], 0, s[22:23]
	s_mov_b32 m0, s48
	s_nop 0
	global_load_lds_dwordx4 v[248:249], off
	v_mfma_f32_32x32x16_bf16 v[50:65], v[216:219], v[224:227], v[50:65]
	v_mfma_f32_32x32x16_bf16 v[34:49], v[220:223], v[224:227], v[34:49]
	v_add_u32_e32 v250, 0x6000, v86
	v_lshl_add_u64 v[248:249], v[66:67], 0, v[0:1]
	v_readfirstlane_b32 s48, v250
	v_lshl_add_u64 v[248:249], v[248:249], 0, s[22:23]
	s_mov_b32 m0, s48
	s_nop 0
	global_load_lds_dwordx4 v[248:249], off
	v_mfma_f32_32x32x16_bf16 v[18:33], v[216:219], v[228:231], v[18:33]
	v_mfma_f32_32x32x16_bf16 v[2:17], v[220:223], v[228:231], v[2:17]
	v_add_u32_e32 v250, 0x3000, v86
	v_lshl_add_u64 v[248:249], v[76:77], 0, v[0:1]
	v_readfirstlane_b32 s48, v250
	v_lshl_add_u64 v[248:249], v[248:249], 0, s[22:23]
	s_mov_b32 m0, s48
	s_nop 0
	global_load_lds_dwordx4 v[248:249], off
	v_mfma_f32_32x32x16_bf16 v[50:65], v[232:235], v[240:243], v[50:65]
	v_mfma_f32_32x32x16_bf16 v[34:49], v[236:239], v[240:243], v[34:49]
	v_add_u32_e32 v250, 0x7000, v86
	v_lshl_add_u64 v[248:249], v[68:69], 0, v[0:1]
	v_readfirstlane_b32 s48, v250
	v_lshl_add_u64 v[248:249], v[248:249], 0, s[22:23]
	s_mov_b32 m0, s48
	s_nop 0
	global_load_lds_dwordx4 v[248:249], off
	v_mfma_f32_32x32x16_bf16 v[18:33], v[232:235], v[244:247], v[18:33]
	v_mfma_f32_32x32x16_bf16 v[2:17], v[236:239], v[244:247], v[2:17]
	s_waitcnt vmcnt(8)
	s_barrier
	s_branch .Ldl_s1

; #define G_WAIT() { asm volatile("s_waitcnt vmcnt(0)" ::: "memory"); __syncthreads(); }
;     ...
;   G_DMA(0, 0);
;   G_WAIT();
;   for (int kt = 0; kt < nk; kt += 2) {
;     if (kt + 1 < nk) G_DMA(1, kt + 1);
;     G_COMPUTE(0);
;     G_WAIT();
;     if (kt + 1 < nk) {
;       if (kt + 2 < nk) G_DMA(0, kt + 2);
;       G_COMPUTE(1);
;       G_WAIT();
;     }
.Ldl_s1:
	ds_read_b128 v[128:131], v160 offset:49152
	ds_read_b128 v[132:135], v160 offset:53248
	ds_read_b128 v[136:139], v192 offset:32768
	ds_read_b128 v[140:143], v192 offset:36864
	ds_read_b128 v[144:147], v161 offset:49152
	ds_read_b128 v[148:151], v161 offset:53248
	ds_read_b128 v[152:155], v193 offset:32768
	ds_read_b128 v[156:159], v193 offset:36864
	ds_read_b128 v[216:219], v190 offset:49152
	ds_read_b128 v[220:223], v190 offset:53248
	ds_read_b128 v[224:227], v194 offset:32768
	ds_read_b128 v[228:231], v194 offset:36864
	ds_read_b128 v[232:235], v191 offset:49152
	ds_read_b128 v[236:239], v191 offset:53248
	ds_read_b128 v[240:243], v195 offset:32768
	ds_read_b128 v[244:247], v195 offset:36864
	s_waitcnt lgkmcnt(0)
	s_barrier
	s_add_i32 s48, s35, 1
	s_cmp_lt_u32 s48, s5
	s_cbranch_scc0 .Ldl_s1_nodma
	v_add_u32_e32 v250, 0x8000, v86
	v_lshl_add_u64 v[248:249], v[80:81], 0, v[0:1]
	v_readfirstlane_b32 s48, v250
	v_lshl_add_u64 v[248:249], v[248:249], 0, s[52:53]
	s_mov_b32 m0, s48
	s_nop 0
	global_load_lds_dwordx4 v[248:249], off
	v_mfma_f32_32x32x16_bf16 v[50:65], v[128:131], v[136:139], v[50:65]
	v_mfma_f32_32x32x16_bf16 v[34:49], v[132:135], v[136:139], v[34:49]
	v_add_u32_e32 v250, 0xc000, v86
	v_lshl_add_u64 v[248:249], v[72:73], 0, v[0:1]
	v_readfirstlane_b32 s48, v250
	v_lshl_add_u64 v[248:249], v[248:249], 0, s[52:53]
	s_mov_b32 m0, s48
	s_nop 0
	global_load_lds_dwordx4 v[248:249], off
	v_mfma_f32_32x32x16_bf16 v[18:33], v[128:131], v[140:143], v[18:33]
	v_mfma_f32_32x32x16_bf16 v[2:17], v[132:135], v[140:143], v[2:17]
	v_add_u32_e32 v250, 0x9000, v86
	v_lshl_add_u64 v[248:249], v[78:79], 0, v[0:1]
	v_readfirstlane_b32 s48, v250
	v_lshl_add_u64 v[248:249], v[248:249], 0, s[52:53]
	s_mov_b32 m0, s48
	s_nop 0
	global_load_lds_dwordx4 v[248:249], off
	v_mfma_f32_32x32x16_bf16 v[50:65], v[144:147], v[152:155], v[50:65]
	v_mfma_f32_32x32x16_bf16 v[34:49], v[148:151], v[152:155], v[34:49]
	v_add_u32_e32 v250, 0xd000, v86
	v_lshl_add_u64 v[248:249], v[70:71], 0, v[0:1]
	v_readfirstlane_b32 s48, v250
	v_lshl_add_u64 v[248:249], v[248:249], 0, s[52:53]
	s_mov_b32 m0, s48
	s_nop 0
	global_load_lds_dwordx4 v[248:249], off
	v_mfma_f32_32x32x16_bf16 v[18:33], v[144:147], v[156:159], v[18:33]
	v_mfma_f32_32x32x16_bf16 v[2:17], v[148:151], v[156:159], v[2:17]
	v_add_u32_e32 v250, 0xa000, v86
	v_lshl_add_u64 v[248:249], v[74:75], 0, v[0:1]
	v_readfirstlane_b32 s48, v250
	v_lshl_add_u64 v[248:249], v[248:249], 0, s[52:53]
	s_mov_b32 m0, s48
	s_nop 0
	global_load_lds_dwordx4 v[248:249], off
	v_mfma_f32_32x32x16_bf16 v[50:65], v[216:219], v[224:227], v[50:65]
	v_mfma_f32_32x32x16_bf16 v[34:49], v[220:223], v[224:227], v[34:49]
	v_add_u32_e32 v250, 0xe000, v86
	v_lshl_add_u64 v[248:249], v[66:67], 0, v[0:1]
	v_readfirstlane_b32 s48, v250
	v_lshl_add_u64 v[248:249], v[248:249], 0, s[52:53]
	s_mov_b32 m0, s48
	s_nop 0
	global_load_lds_dwordx4 v[248:249], off
	v_mfma_f32_32x32x16_bf16 v[18:33], v[216:219], v[228:231], v[18:33]
	v_mfma_f32_32x32x16_bf16 v[2:17], v[220:223], v[228:231], v[2:17]
	v_add_u32_e32 v250, 0xb000, v86
	v_lshl_add_u64 v[248:249], v[76:77], 0, v[0:1]
	v_readfirstlane_b32 s48, v250
	v_lshl_add_u64 v[248:249], v[248:249], 0, s[52:53]
	s_mov_b32 m0, s48
	s_nop 0
	global_load_lds_dwordx4 v[248:249], off
	v_mfma_f32_32x32x16_bf16 v[50:65], v[232:235], v[240:243], v[50:65]
	v_mfma_f32_32x32x16_bf16 v[34:49], v[236:239], v[240:243], v[34:49]
	v_add_u32_e32 v250, 0xf000, v86
	v_lshl_add_u64 v[248:249], v[68:69], 0, v[0:1]
	v_readfirstlane_b32 s48, v250
	v_lshl_add_u64 v[248:249], v[248:249], 0, s[52:53]
	s_mov_b32 m0, s48
	s_nop 0
	global_load_lds_dwordx4 v[248:249], off
	v_mfma_f32_32x32x16_bf16 v[18:33], v[232:235], v[244:247], v[18:33]
	v_mfma_f32_32x32x16_bf16 v[2:17], v[236:239], v[244:247], v[2:17]
	s_waitcnt vmcnt(8)
	s_barrier
	s_branch .Ldl_next
